# v63: v61 + next P3 queue ticket fetched during the FoX item epilogue (atomic round trip hidden)
# baseline (speedup 1.0000x reference)
; __global__ void __launch_bounds__(512, 2) fwd_mega(Params P) {
;     ...
;     for (;;) {
;         PHASE_IDS
;         int pr;
;         if (first) { first = false; pr = bid; }
;         else {
;             __syncthreads();
;             if (tid == 0) *s_item = nblk + atomicAdd((int*)(ws + OFF_CTR) + rep, 1);
;             __syncthreads();
;             pr = *s_item;
;         }
;         if (pr >= 64 + 512) break;
.LBB0_532:
	v_mbcnt_lo_u32_b32 v10, -1, 0
	v_mbcnt_hi_u32_b32 v10, -1, v10
	s_and_b64 vcc, exec, s[0:1]
	v_add_u32_e32 v24, s84, v10
	v_mov_b32_e32 v25, s33
	s_cbranch_vccnz .LBB0_538
	v_cmp_eq_u32_e32 vcc, 0, v24
	s_barrier
	s_and_saveexec_b64 s[0:1], vcc
	s_cbranch_execz .LBB0_537
	s_mov_b64 s[26:27], exec
	v_mbcnt_lo_u32_b32 v0, s26, 0
	v_mbcnt_hi_u32_b32 v0, s27, v0
	v_cmp_eq_u32_e32 vcc, 0, v0
	s_and_saveexec_b64 s[2:3], vcc
	s_cbranch_execz .LBB0_536
	s_waitcnt vmcnt(0)
	v_mov_b32_e32 v2, v254

; __global__ void __launch_bounds__(512, 2) fwd_mega(Params P) {
;     ...
;             if (tid == 0) *s_item = nblk + atomicAdd((int*)(ws + OFF_CTR) + rep, 1);
;     ...
;         else { const int fj = pr - 64; fox_attn(P, (fj & 31) * 2 + team, 15 - (fj >> 5), smem, tt); }
.LBB0_557:
	s_or_b64 exec, exec, s[30:31]
	s_cmp_lg_u32 s84, 0
	s_cbranch_scc1 .Ltk_fox_skip
	s_mov_b64 s[64:65], exec
	s_mov_b64 exec, 1
	v_mov_b32_e32 v253, 1
	global_atomic_add v254, v1, v253, s[4:5] sc0
	s_mov_b64 exec, s[64:65]

; __global__ void __launch_bounds__(512, 2) fwd_mega(Params P) {
;     ...
;             if (tid == 0) *s_item = nblk + atomicAdd((int*)(ws + OFF_CTR) + rep, 1);
;     ...
;         if (pr < 64) gdn_scan(P, pr * 2 + team, smem, tt);
.Lscan_done:
	s_waitcnt vmcnt(0)
	s_barrier
	s_cmp_lg_u32 s84, 0
	s_cbranch_scc1 .LBB0_530
	buffer_wbl2 sc1
	s_waitcnt vmcnt(0)
	s_add_u32 s66, s80, 0x1d83c00
	s_addc_u32 s67, s81, 0
	s_mov_b64 s[64:65], exec
	s_mov_b64 exec, 1
	v_mov_b32_e32 v190, 0
	v_mov_b32_e32 v191, 1
	global_atomic_add v190, v191, s[66:67]
	v_mov_b32_e32 v253, 1
	global_atomic_add v254, v1, v253, s[4:5] sc0
	s_mov_b64 exec, s[64:65]
	s_branch .LBB0_530
